# mode-A: next-tile QK MFMAs take the -mhat C operand from the live registers, 8 v_mov_b64 per tile removed (on top of static priority stack)
# baseline (speedup 1.0000x reference)
; __device__ __forceinline__ float fast_exp2(float x) { return __builtin_amdgcn_exp2f(x); }
; template <int DQK, int DV, int MODE>
; __device__ __forceinline__ void attn_item(LAS unsigned char* lds, int item, const AttnCtx& cx) {
;     ...
;             const float delta = first ? mx : fmaxf(mx, 0.f), alpha = fast_exp2(-delta);
; #pragma unroll
;             for (int i = 0; i < 16; ++i) { s0[i] -= delta; s1[i] -= delta; }
;             if (!first) {
; #pragma unroll
;                 for (int d = 0; d < NDV; ++d)
; #pragma unroll
;                     for (int i = 0; i < 16; ++i) O[d][i] *= alpha;
; #pragma unroll
;                 for (int i = 0; i < 16; ++i) Lacc[i] *= alpha;
;             }
;             mhat += delta;
; #pragma unroll
;             for (int i = 0; i < 16; ++i) negm[i] = -mhat;
;             if (MODE == 1) set_cin();
;             first = false;
.LBB0_255:
	v_add_f32_e32 v212, v212, v114
	v_xor_b32_e32 v130, 0x80000000, v212
	v_pk_add_f32 v[82:83], v[82:83], v[114:115] op_sel_hi:[1,0] neg_lo:[0,1] neg_hi:[0,1]
	v_pk_add_f32 v[98:99], v[98:99], v[114:115] op_sel_hi:[1,0] neg_lo:[0,1] neg_hi:[0,1]
	v_pk_add_f32 v[84:85], v[84:85], v[114:115] op_sel_hi:[1,0] neg_lo:[0,1] neg_hi:[0,1]
	v_pk_add_f32 v[100:101], v[100:101], v[114:115] op_sel_hi:[1,0] neg_lo:[0,1] neg_hi:[0,1]
	v_pk_add_f32 v[86:87], v[86:87], v[114:115] op_sel_hi:[1,0] neg_lo:[0,1] neg_hi:[0,1]
	v_pk_add_f32 v[102:103], v[102:103], v[114:115] op_sel_hi:[1,0] neg_lo:[0,1] neg_hi:[0,1]
	v_pk_add_f32 v[88:89], v[88:89], v[114:115] op_sel_hi:[1,0] neg_lo:[0,1] neg_hi:[0,1]
	v_pk_add_f32 v[104:105], v[104:105], v[114:115] op_sel_hi:[1,0] neg_lo:[0,1] neg_hi:[0,1]
	v_pk_add_f32 v[90:91], v[90:91], v[114:115] op_sel_hi:[1,0] neg_lo:[0,1] neg_hi:[0,1]
	v_pk_add_f32 v[106:107], v[106:107], v[114:115] op_sel_hi:[1,0] neg_lo:[0,1] neg_hi:[0,1]
	v_pk_add_f32 v[92:93], v[92:93], v[114:115] op_sel_hi:[1,0] neg_lo:[0,1] neg_hi:[0,1]
	v_pk_add_f32 v[108:109], v[108:109], v[114:115] op_sel_hi:[1,0] neg_lo:[0,1] neg_hi:[0,1]
	v_pk_add_f32 v[94:95], v[94:95], v[114:115] op_sel_hi:[1,0] neg_lo:[0,1] neg_hi:[0,1]
	v_pk_add_f32 v[110:111], v[110:111], v[114:115] op_sel_hi:[1,0] neg_lo:[0,1] neg_hi:[0,1]
	v_pk_add_f32 v[96:97], v[96:97], v[114:115] op_sel_hi:[1,0] neg_lo:[0,1] neg_hi:[0,1]
	v_pk_add_f32 v[112:113], v[112:113], v[114:115] op_sel_hi:[1,0] neg_lo:[0,1] neg_hi:[0,1]
	v_mov_b32_e32 v131, v130
	v_mov_b32_e32 v129, v130
	v_mov_b32_e32 v128, v130
	v_mov_b32_e32 v127, v130
	v_mov_b32_e32 v126, v130
	v_mov_b32_e32 v125, v130
	v_mov_b32_e32 v124, v130
	v_mov_b32_e32 v123, v130
	v_mov_b32_e32 v122, v130
	v_mov_b32_e32 v121, v130
	v_mov_b32_e32 v120, v130
	v_mov_b32_e32 v119, v130
	v_mov_b32_e32 v118, v130
	v_mov_b32_e32 v117, v130
	v_mov_b32_e32 v116, v130
	v_mov_b32_e32 v115, v130
	v_mov_b32_e32 v114, v130
	s_branch .LBB0_257
; #define SBAR() __builtin_amdgcn_sched_barrier(0)
; template <int DQK, int DV, int MODE>
; __device__ __forceinline__ void attn_item(LAS unsigned char* lds, int item, const AttnCtx& cx) {
;     ...
;     auto do_qk = [&](int j, bool vpre) {
;         const unsigned kaddr = (unsigned)(size_t)(lds + (j % NST) * SB + koff) + r * KP + 16 * h;
;         const unsigned va = vaddr_of(j);
;         bf16x8 kfr[1][4];
;         K_ISSUE(0, 0);
; #pragma unroll
;         for (int kb = 0; kb < NQF / 2; ++kb) {
;             LGKM0(); SBAR();
;             if (kb == 0) { if (MODE == 1) { s0 = MFMA32(kfr[0][0], qf[0], cin0); s1 = MFMA32(kfr[0][1], qf[0], cin1); } else { s0 = MFMA32(kfr[0][0], qf[0], negm); s1 = MFMA32(kfr[0][1], qf[0], negm); } }
;             else { s0 = MFMA32(kfr[0][0], qf[2 * kb], s0); s1 = MFMA32(kfr[0][1], qf[2 * kb], s1); }
;             s0 = MFMA32(kfr[0][2], qf[2 * kb + 1], s0); s1 = MFMA32(kfr[0][3], qf[2 * kb + 1], s1);
;             SBAR();
;             if (kb + 1 < NQF / 2) K_ISSUE(0, kb + 1); else if (vpre) V_ISSUE(va, 0, 0);
;         }
;     ...
;         for (int i = 0; i < 16; ++i) { s0[i] = fast_exp2(s0[i]); s1[i] = fast_exp2(s1[i]); }
;         u32x4 w;
;         w.x = pk2(s0[0], s0[1]); w.y = pk2(s0[2], s0[3]); w.z = pk2(s0[4], s0[5]); w.w = pk2(s0[6], s0[7]); pa[0][0] = __builtin_bit_cast(bf16x8, w);
;         w.x = pk2(s0[8], s0[9]); w.y = pk2(s0[10], s0[11]); w.z = pk2(s0[12], s0[13]); w.w = pk2(s0[14], s0[15]); pa[0][1] = __builtin_bit_cast(bf16x8, w);
;         w.x = pk2(s1[0], s1[1]); w.y = pk2(s1[2], s1[3]); w.z = pk2(s1[4], s1[5]); w.w = pk2(s1[6], s1[7]); pa[1][0] = __builtin_bit_cast(bf16x8, w);
;         w.x = pk2(s1[8], s1[9]); w.y = pk2(s1[10], s1[11]); w.z = pk2(s1[12], s1[13]); w.w = pk2(s1[14], s1[15]); pa[1][1] = __builtin_bit_cast(bf16x8, w);
;     };
;     auto do_pv = [&](unsigned va) {
; #pragma unroll
;         for (int k4 = 0; k4 < 4; ++k4) Lacc = MFMA32(ones8, pa[k4 >> 1][k4 & 1], Lacc);
; #pragma unroll
;         for (int d = 0; d < NDV; ++d) {
;             LGKM0(); SBAR();
; #pragma unroll
;             for (int k4 = 0; k4 < 4; ++k4) {
;                 const bf16x8 vf = __builtin_shufflevector(vlo[d & 1][k4], vhi[d & 1][k4], 0, 1, 2, 3, 4, 5, 6, 7);
;                 O[d] = MFMA32(vf, pa[k4 >> 1][k4 & 1], O[d]);
;             }
;             SBAR();
;             if (d + 1 < NDV) V_ISSUE(va, (d + 1) & 1, d + 1);
.LBB0_256:
.LBB0_257:
	s_mov_b32 s90, s88
	s_mov_b32 s91, s88
	s_mov_b32 s89, s88
	v_mov_b64_e32 v[228:229], s[90:91]
	v_exp_f32_e32 v82, v82
	v_exp_f32_e32 v83, v83
	v_exp_f32_e32 v84, v84
	v_exp_f32_e32 v85, v85
	v_exp_f32_e32 v86, v86
	v_exp_f32_e32 v87, v87
	v_exp_f32_e32 v88, v88
	v_exp_f32_e32 v89, v89
	v_mov_b64_e32 v[226:227], s[88:89]
	v_cvt_pk_bf16_f32 v230, v82, v83
	v_cvt_pk_bf16_f32 v231, v84, v85
	v_cvt_pk_bf16_f32 v232, v86, v87
	v_cvt_pk_bf16_f32 v233, v88, v89
	v_exp_f32_e32 v90, v90
	v_exp_f32_e32 v91, v91
	v_mfma_f32_32x32x16_bf16 v[66:81], v[226:229], v[230:233], v[66:81]
	v_exp_f32_e32 v92, v92
	v_exp_f32_e32 v93, v93
	v_exp_f32_e32 v94, v94
	v_exp_f32_e32 v95, v95
	v_exp_f32_e32 v96, v96
	v_exp_f32_e32 v97, v97
	v_cvt_pk_bf16_f32 v234, v90, v91
	v_cvt_pk_bf16_f32 v235, v92, v93
	v_cvt_pk_bf16_f32 v236, v94, v95
	v_cvt_pk_bf16_f32 v237, v96, v97
	v_exp_f32_e32 v98, v98
	v_exp_f32_e32 v99, v99
	v_mfma_f32_32x32x16_bf16 v[66:81], v[226:229], v[234:237], v[66:81]
	v_exp_f32_e32 v100, v100
	v_exp_f32_e32 v101, v101
	v_exp_f32_e32 v102, v102
	v_exp_f32_e32 v103, v103
	v_exp_f32_e32 v104, v104
	v_exp_f32_e32 v105, v105
	v_cvt_pk_bf16_f32 v238, v98, v99
	v_cvt_pk_bf16_f32 v239, v100, v101
	v_cvt_pk_bf16_f32 v240, v102, v103
	v_cvt_pk_bf16_f32 v241, v104, v105
	v_exp_f32_e32 v106, v106
	v_exp_f32_e32 v107, v107
	v_mfma_f32_32x32x16_bf16 v[66:81], v[226:229], v[238:241], v[66:81]
	v_exp_f32_e32 v108, v108
	v_exp_f32_e32 v109, v109
	v_exp_f32_e32 v110, v110
	v_exp_f32_e32 v111, v111
	v_exp_f32_e32 v112, v112
	v_exp_f32_e32 v113, v113
	v_cvt_pk_bf16_f32 v242, v106, v107
	v_cvt_pk_bf16_f32 v243, v108, v109
	v_cvt_pk_bf16_f32 v244, v110, v111
	v_cvt_pk_bf16_f32 v245, v112, v113
	s_and_b32 s3, s82, 3
	s_mul_i32 s3, s3, 0x9800
	v_mfma_f32_32x32x16_bf16 v[66:81], v[226:229], v[242:245], v[66:81]
	s_waitcnt lgkmcnt(0)
	s_add_i32 s3, s3, 0
	s_addk_i32 s3, 0x4800
	v_add_u32_e32 v213, s3, v203
	v_mfma_f32_32x32x16_bf16 v[50:65], v[162:165], v[230:233], v[50:65]
	v_mfma_f32_32x32x16_bf16 v[50:65], v[166:169], v[234:237], v[50:65]
	v_mfma_f32_32x32x16_bf16 v[50:65], v[170:173], v[238:241], v[50:65]
	v_mfma_f32_32x32x16_bf16 v[50:65], v[174:177], v[242:245], v[50:65]
	ds_read_b64_tr_b16 v[162:163], v213 offset:64
	ds_read_b64_tr_b16 v[164:165], v213 offset:2624
	ds_read_b64_tr_b16 v[166:167], v213 offset:5184
	ds_read_b64_tr_b16 v[168:169], v213 offset:7744
	ds_read_b64_tr_b16 v[170:171], v213 offset:10304
	ds_read_b64_tr_b16 v[172:173], v213 offset:12864
	ds_read_b64_tr_b16 v[174:175], v213 offset:15424
	ds_read_b64_tr_b16 v[176:177], v213 offset:17984
	s_waitcnt lgkmcnt(0)
	s_nop 0
	v_mfma_f32_32x32x16_bf16 v[34:49], v[162:165], v[230:233], v[34:49]
	v_mfma_f32_32x32x16_bf16 v[34:49], v[166:169], v[234:237], v[34:49]
	v_mfma_f32_32x32x16_bf16 v[34:49], v[170:173], v[238:241], v[34:49]
	v_mfma_f32_32x32x16_bf16 v[34:49], v[174:177], v[242:245], v[34:49]
	ds_read_b64_tr_b16 v[162:163], v213 offset:128
	ds_read_b64_tr_b16 v[164:165], v213 offset:2688
	ds_read_b64_tr_b16 v[166:167], v213 offset:5248
	ds_read_b64_tr_b16 v[168:169], v213 offset:7808
	ds_read_b64_tr_b16 v[170:171], v213 offset:10368
	ds_read_b64_tr_b16 v[172:173], v213 offset:12928
	ds_read_b64_tr_b16 v[174:175], v213 offset:15488
	ds_read_b64_tr_b16 v[176:177], v213 offset:18048
	s_waitcnt lgkmcnt(0)
	s_nop 0
	v_mfma_f32_32x32x16_bf16 v[18:33], v[162:165], v[230:233], v[18:33]
	v_mfma_f32_32x32x16_bf16 v[18:33], v[166:169], v[234:237], v[18:33]
	v_mfma_f32_32x32x16_bf16 v[18:33], v[170:173], v[238:241], v[18:33]
	v_mfma_f32_32x32x16_bf16 v[18:33], v[174:177], v[242:245], v[18:33]
	ds_read_b64_tr_b16 v[226:227], v213 offset:192
	ds_read_b64_tr_b16 v[228:229], v213 offset:2752
	ds_read_b64_tr_b16 v[246:247], v213 offset:5312
	ds_read_b64_tr_b16 v[248:249], v213 offset:7872
	ds_read_b64_tr_b16 v[222:223], v213 offset:10432
	ds_read_b64_tr_b16 v[224:225], v213 offset:12992
	ds_read_b64_tr_b16 v[214:215], v213 offset:15552
	ds_read_b64_tr_b16 v[216:217], v213 offset:18112
	s_waitcnt lgkmcnt(0)
	s_nop 0
	v_mfma_f32_32x32x16_bf16 v[2:17], v[226:229], v[230:233], v[2:17]
	v_mfma_f32_32x32x16_bf16 v[2:17], v[246:249], v[234:237], v[2:17]
	v_mfma_f32_32x32x16_bf16 v[2:17], v[222:225], v[238:241], v[2:17]
	v_mfma_f32_32x32x16_bf16 v[2:17], v[214:217], v[242:245], v[2:17]
	s_add_i32 s82, s82, 1
	s_cmp_ge_u32 s82, s83
	s_cselect_b64 s[50:51], -1, 0
	s_or_b64 s[50:51], s[24:25], s[50:51]
	s_and_b64 vcc, exec, s[50:51]
	s_cbranch_vccnz .LBB0_200
	s_and_b32 s3, s82, 3
	s_mul_i32 s3, s3, 0x9800
	s_add_i32 s3, s77, s3
	v_add_u32_e32 v213, s3, v202
	ds_read_b128 v[98:101], v213 offset:0
	ds_read_b128 v[102:105], v213 offset:4608
	ds_read_b128 v[106:109], v213 offset:32
	ds_read_b128 v[110:113], v213 offset:4640
	s_waitcnt lgkmcnt(0)
	s_nop 0
	v_mfma_f32_32x32x16_bf16 v[82:97], v[98:101], v[146:149], v[114:129]
	v_mfma_f32_32x32x16_bf16 v[130:145], v[102:105], v[146:149], v[114:129]
	v_mfma_f32_32x32x16_bf16 v[82:97], v[106:109], v[150:153], v[82:97]
	v_mfma_f32_32x32x16_bf16 v[130:145], v[110:113], v[150:153], v[130:145]
	ds_read_b128 v[98:101], v213 offset:64
	ds_read_b128 v[102:105], v213 offset:4672
	ds_read_b128 v[106:109], v213 offset:96
	ds_read_b128 v[110:113], v213 offset:4704
	s_waitcnt lgkmcnt(0)
	s_nop 0
	v_mfma_f32_32x32x16_bf16 v[82:97], v[98:101], v[154:157], v[82:97]
	v_mfma_f32_32x32x16_bf16 v[130:145], v[102:105], v[154:157], v[130:145]
	v_mfma_f32_32x32x16_bf16 v[82:97], v[106:109], v[158:161], v[82:97]
	v_mfma_f32_32x32x16_bf16 v[130:145], v[110:113], v[158:161], v[130:145]
	s_nop 11
	v_mov_b32_e32 v98, v130
	v_mov_b32_e32 v99, v131
	v_mov_b32_e32 v100, v132
	v_mov_b32_e32 v101, v133
	v_mov_b32_e32 v102, v134
	v_mov_b32_e32 v103, v135
	v_mov_b32_e32 v104, v136
	v_mov_b32_e32 v105, v137
	v_mov_b32_e32 v106, v138
	v_mov_b32_e32 v107, v139
	v_mov_b32_e32 v108, v140
	v_mov_b32_e32 v109, v141
	v_mov_b32_e32 v110, v142
	v_mov_b32_e32 v111, v143
	v_mov_b32_e32 v112, v144
	v_mov_b32_e32 v113, v145
	s_branch .LBB0_200
